# EpiSwiglu epilogue: silu chains regenerated 4-wide interleaved with packed mul/add, no hazard nops, fresh temporaries (bit-identical math)
# baseline (speedup 1.0000x reference)
; __device__ __forceinline__ float silu_f(float x) { return x * __builtin_amdgcn_rcpf(1.0f + fexp(-x)); }
;     __device__ __forceinline__ void operator()(const f32x4 (&acc)[2][2][4][2], const Unit& u, int wr, int wc, int fr, int fq) const {
;         const int row0 = u.pm * BM + wr * 64 + fr, col0 = u.pn * 128 + wc * 32 + 8 * fq;
; #pragma unroll
;         for (int ai = 0; ai < 2; ++ai)
; #pragma unroll
;             for (int m = 0; m < 4; ++m) {
;                 h16x8 o;
; #pragma unroll
;                 for (int n = 0; n < 2; ++n)
; #pragma unroll
;                     for (int j = 0; j < 4; ++j) o[4 * n + j] = (h16)(silu_f(acc[ai][0][m][n][j]) * acc[ai][1][m][n][j]);
;                 *(h16x8*)(O + (unsigned)(row0 + ai * HALF + m * 16) * FF + col0) = o;
;             }
;     }
.LBB0_756:
	s_mov_b32 s18, 0xbfb8aa3b
	s_mov_b32 s19, 0xbfb8aa3b
	v_lshl_add_u32 v32, s16, 8, v142
	v_lshl_or_b32 v146, s17, 7, v144
	s_movk_i32 s9, 0xb00
	v_ashrrev_i32_e32 v147, 31, v146
	v_mul_lo_u32 v32, v32, s9
	s_mov_b64 s[16:17], -1
	s_andn2_b64 vcc, exec, s[4:5]
	v_lshl_add_u64 v[230:231], v[32:33], 1, s[86:87]
	v_lshlrev_b64 v[232:233], 1, v[146:147]
	v_lshl_add_u64 v[230:231], v[230:231], 0, v[232:233]
	v_pk_mul_f32 v[150:151], v[126:127], s[18:19]
	v_pk_mul_f32 v[152:153], v[128:129], s[18:19]
	v_pk_mul_f32 v[154:155], v[118:119], s[18:19]
	v_pk_mul_f32 v[156:157], v[120:121], s[18:19]
	v_exp_f32_e32 v150, v150
	v_exp_f32_e32 v152, v152
	v_exp_f32_e32 v154, v154
	v_exp_f32_e32 v156, v156
	v_exp_f32_e32 v151, v151
	v_exp_f32_e32 v153, v153
	v_exp_f32_e32 v155, v155
	v_exp_f32_e32 v157, v157
	v_pk_add_f32 v[150:151], v[150:151], 1.0 op_sel_hi:[1,0]
	v_pk_add_f32 v[152:153], v[152:153], 1.0 op_sel_hi:[1,0]
	v_pk_add_f32 v[154:155], v[154:155], 1.0 op_sel_hi:[1,0]
	v_pk_add_f32 v[156:157], v[156:157], 1.0 op_sel_hi:[1,0]
	v_rcp_f32_e32 v150, v150
	v_rcp_f32_e32 v152, v152
	v_rcp_f32_e32 v154, v154
	v_rcp_f32_e32 v156, v156
	v_rcp_f32_e32 v151, v151
	v_rcp_f32_e32 v153, v153
	v_rcp_f32_e32 v155, v155
	v_rcp_f32_e32 v157, v157
	v_pk_mul_f32 v[150:151], v[126:127], v[150:151]
	v_pk_mul_f32 v[152:153], v[128:129], v[152:153]
	v_pk_mul_f32 v[154:155], v[118:119], v[154:155]
	v_pk_mul_f32 v[156:157], v[120:121], v[156:157]
	v_pk_mul_f32 v[150:151], v[150:151], v[122:123]
	v_pk_mul_f32 v[152:153], v[152:153], v[124:125]
	v_pk_mul_f32 v[154:155], v[154:155], v[114:115]
	v_pk_mul_f32 v[156:157], v[156:157], v[116:117]
	v_cvt_pk_f16_f32 v122, v150, v151
	v_cvt_pk_f16_f32 v123, v152, v153
	v_cvt_pk_f16_f32 v124, v154, v155
	v_cvt_pk_f16_f32 v125, v156, v157
	s_nop 0
	global_store_dwordx4 v[230:231], v[122:125], off
	v_add_u32_e32 v234, 0xb000, v32
	v_mov_b32_e32 v235, v33
	v_lshl_add_u64 v[234:235], v[234:235], 1, s[86:87]
	v_lshl_add_u64 v[234:235], v[234:235], 0, v[232:233]
	v_pk_mul_f32 v[158:159], v[110:111], s[18:19]
	v_pk_mul_f32 v[160:161], v[112:113], s[18:19]
	v_pk_mul_f32 v[162:163], v[102:103], s[18:19]
	v_pk_mul_f32 v[164:165], v[104:105], s[18:19]
	v_exp_f32_e32 v158, v158
	v_exp_f32_e32 v160, v160
	v_exp_f32_e32 v162, v162
	v_exp_f32_e32 v164, v164
	v_exp_f32_e32 v159, v159
	v_exp_f32_e32 v161, v161
	v_exp_f32_e32 v163, v163
	v_exp_f32_e32 v165, v165
	v_pk_add_f32 v[158:159], v[158:159], 1.0 op_sel_hi:[1,0]
	v_pk_add_f32 v[160:161], v[160:161], 1.0 op_sel_hi:[1,0]
	v_pk_add_f32 v[162:163], v[162:163], 1.0 op_sel_hi:[1,0]
	v_pk_add_f32 v[164:165], v[164:165], 1.0 op_sel_hi:[1,0]
	v_rcp_f32_e32 v158, v158
	v_rcp_f32_e32 v160, v160
	v_rcp_f32_e32 v162, v162
	v_rcp_f32_e32 v164, v164
	v_rcp_f32_e32 v159, v159
	v_rcp_f32_e32 v161, v161
	v_rcp_f32_e32 v163, v163
	v_rcp_f32_e32 v165, v165
	v_pk_mul_f32 v[158:159], v[110:111], v[158:159]
	v_pk_mul_f32 v[160:161], v[112:113], v[160:161]
	v_pk_mul_f32 v[162:163], v[102:103], v[162:163]
	v_pk_mul_f32 v[164:165], v[104:105], v[164:165]
	v_pk_mul_f32 v[158:159], v[158:159], v[106:107]
	v_pk_mul_f32 v[160:161], v[160:161], v[108:109]
	v_pk_mul_f32 v[162:163], v[162:163], v[98:99]
	v_pk_mul_f32 v[164:165], v[164:165], v[100:101]
	v_cvt_pk_f16_f32 v106, v158, v159
	v_cvt_pk_f16_f32 v107, v160, v161
	v_cvt_pk_f16_f32 v108, v162, v163
	v_cvt_pk_f16_f32 v109, v164, v165
	s_nop 0
	global_store_dwordx4 v[234:235], v[106:109], off
	v_add_u32_e32 v236, 0x16000, v32
	v_mov_b32_e32 v237, v33
	v_lshl_add_u64 v[236:237], v[236:237], 1, s[86:87]
	v_lshl_add_u64 v[236:237], v[236:237], 0, v[232:233]
	v_pk_mul_f32 v[150:151], v[94:95], s[18:19]
	v_pk_mul_f32 v[152:153], v[96:97], s[18:19]
	v_pk_mul_f32 v[154:155], v[86:87], s[18:19]
	v_pk_mul_f32 v[156:157], v[88:89], s[18:19]
	v_exp_f32_e32 v150, v150
	v_exp_f32_e32 v152, v152
	v_exp_f32_e32 v154, v154
	v_exp_f32_e32 v156, v156
	v_exp_f32_e32 v151, v151
	v_exp_f32_e32 v153, v153
	v_exp_f32_e32 v155, v155
	v_exp_f32_e32 v157, v157
	v_pk_add_f32 v[150:151], v[150:151], 1.0 op_sel_hi:[1,0]
	v_pk_add_f32 v[152:153], v[152:153], 1.0 op_sel_hi:[1,0]
	v_pk_add_f32 v[154:155], v[154:155], 1.0 op_sel_hi:[1,0]
	v_pk_add_f32 v[156:157], v[156:157], 1.0 op_sel_hi:[1,0]
	v_rcp_f32_e32 v150, v150
	v_rcp_f32_e32 v152, v152
	v_rcp_f32_e32 v154, v154
	v_rcp_f32_e32 v156, v156
	v_rcp_f32_e32 v151, v151
	v_rcp_f32_e32 v153, v153
	v_rcp_f32_e32 v155, v155
	v_rcp_f32_e32 v157, v157
	v_pk_mul_f32 v[150:151], v[94:95], v[150:151]
	v_pk_mul_f32 v[152:153], v[96:97], v[152:153]
	v_pk_mul_f32 v[154:155], v[86:87], v[154:155]
	v_pk_mul_f32 v[156:157], v[88:89], v[156:157]
	v_pk_mul_f32 v[150:151], v[150:151], v[90:91]
	v_pk_mul_f32 v[152:153], v[152:153], v[92:93]
	v_pk_mul_f32 v[154:155], v[154:155], v[82:83]
	v_pk_mul_f32 v[156:157], v[156:157], v[84:85]
	v_cvt_pk_f16_f32 v90, v150, v151
	v_cvt_pk_f16_f32 v91, v152, v153
	v_cvt_pk_f16_f32 v92, v154, v155
	v_cvt_pk_f16_f32 v93, v156, v157
	s_nop 0
	global_store_dwordx4 v[236:237], v[90:93], off
	v_add_u32_e32 v238, 0x21000, v32
	v_mov_b32_e32 v239, v33
	v_lshl_add_u64 v[238:239], v[238:239], 1, s[86:87]
	v_lshl_add_u64 v[238:239], v[238:239], 0, v[232:233]
	v_pk_mul_f32 v[158:159], v[78:79], s[18:19]
	v_pk_mul_f32 v[160:161], v[80:81], s[18:19]
	v_pk_mul_f32 v[162:163], v[70:71], s[18:19]
	v_pk_mul_f32 v[164:165], v[72:73], s[18:19]
	v_exp_f32_e32 v158, v158
	v_exp_f32_e32 v160, v160
	v_exp_f32_e32 v162, v162
	v_exp_f32_e32 v164, v164
	v_exp_f32_e32 v159, v159
	v_exp_f32_e32 v161, v161
	v_exp_f32_e32 v163, v163
	v_exp_f32_e32 v165, v165
	v_pk_add_f32 v[158:159], v[158:159], 1.0 op_sel_hi:[1,0]
	v_pk_add_f32 v[160:161], v[160:161], 1.0 op_sel_hi:[1,0]
; __device__ __forceinline__ float silu_f(float x) { return x * __builtin_amdgcn_rcpf(1.0f + fexp(-x)); }
;     __device__ __forceinline__ void operator()(const f32x4 (&acc)[2][2][4][2], const Unit& u, int wr, int wc, int fr, int fq) const {
;         const int row0 = u.pm * BM + wr * 64 + fr, col0 = u.pn * 128 + wc * 32 + 8 * fq;
; #pragma unroll
;         for (int ai = 0; ai < 2; ++ai)
; #pragma unroll
;             for (int m = 0; m < 4; ++m) {
;                 h16x8 o;
; #pragma unroll
;                 for (int n = 0; n < 2; ++n)
; #pragma unroll
;                     for (int j = 0; j < 4; ++j) o[4 * n + j] = (h16)(silu_f(acc[ai][0][m][n][j]) * acc[ai][1][m][n][j]);
;                 *(h16x8*)(O + (unsigned)(row0 + ai * HALF + m * 16) * FF + col0) = o;
;             }
;     }
	v_pk_add_f32 v[162:163], v[162:163], 1.0 op_sel_hi:[1,0]
	v_pk_add_f32 v[164:165], v[164:165], 1.0 op_sel_hi:[1,0]
	v_rcp_f32_e32 v158, v158
	v_rcp_f32_e32 v160, v160
	v_rcp_f32_e32 v162, v162
	v_rcp_f32_e32 v164, v164
	v_rcp_f32_e32 v159, v159
	v_rcp_f32_e32 v161, v161
	v_rcp_f32_e32 v163, v163
	v_rcp_f32_e32 v165, v165
	v_pk_mul_f32 v[158:159], v[78:79], v[158:159]
	v_pk_mul_f32 v[160:161], v[80:81], v[160:161]
	v_pk_mul_f32 v[162:163], v[70:71], v[162:163]
	v_pk_mul_f32 v[164:165], v[72:73], v[164:165]
	v_pk_mul_f32 v[158:159], v[158:159], v[74:75]
	v_pk_mul_f32 v[160:161], v[160:161], v[76:77]
	v_pk_mul_f32 v[162:163], v[162:163], v[66:67]
	v_pk_mul_f32 v[164:165], v[164:165], v[68:69]
	v_cvt_pk_f16_f32 v74, v158, v159
	v_cvt_pk_f16_f32 v75, v160, v161
	v_cvt_pk_f16_f32 v76, v162, v163
	v_cvt_pk_f16_f32 v77, v164, v165
	s_nop 0
	global_store_dwordx4 v[238:239], v[74:77], off
	v_add_u32_e32 v240, 0x58000, v32
	v_mov_b32_e32 v241, v33
	v_lshl_add_u64 v[240:241], v[240:241], 1, s[86:87]
	v_lshl_add_u64 v[240:241], v[240:241], 0, v[232:233]
	v_pk_mul_f32 v[150:151], v[62:63], s[18:19]
	v_pk_mul_f32 v[152:153], v[64:65], s[18:19]
	v_pk_mul_f32 v[154:155], v[54:55], s[18:19]
	v_pk_mul_f32 v[156:157], v[56:57], s[18:19]
	v_exp_f32_e32 v150, v150
	v_exp_f32_e32 v152, v152
	v_exp_f32_e32 v154, v154
	v_exp_f32_e32 v156, v156
	v_exp_f32_e32 v151, v151
	v_exp_f32_e32 v153, v153
	v_exp_f32_e32 v155, v155
	v_exp_f32_e32 v157, v157
	v_pk_add_f32 v[150:151], v[150:151], 1.0 op_sel_hi:[1,0]
	v_pk_add_f32 v[152:153], v[152:153], 1.0 op_sel_hi:[1,0]
	v_pk_add_f32 v[154:155], v[154:155], 1.0 op_sel_hi:[1,0]
	v_pk_add_f32 v[156:157], v[156:157], 1.0 op_sel_hi:[1,0]
	v_rcp_f32_e32 v150, v150
	v_rcp_f32_e32 v152, v152
	v_rcp_f32_e32 v154, v154
	v_rcp_f32_e32 v156, v156
	v_rcp_f32_e32 v151, v151
	v_rcp_f32_e32 v153, v153
	v_rcp_f32_e32 v155, v155
	v_rcp_f32_e32 v157, v157
	v_pk_mul_f32 v[150:151], v[62:63], v[150:151]
	v_pk_mul_f32 v[152:153], v[64:65], v[152:153]
	v_pk_mul_f32 v[154:155], v[54:55], v[154:155]
	v_pk_mul_f32 v[156:157], v[56:57], v[156:157]
	v_pk_mul_f32 v[150:151], v[150:151], v[58:59]
	v_pk_mul_f32 v[152:153], v[152:153], v[60:61]
	v_pk_mul_f32 v[154:155], v[154:155], v[50:51]
	v_pk_mul_f32 v[156:157], v[156:157], v[52:53]
	v_cvt_pk_f16_f32 v58, v150, v151
	v_cvt_pk_f16_f32 v59, v152, v153
	v_cvt_pk_f16_f32 v60, v154, v155
	v_cvt_pk_f16_f32 v61, v156, v157
	s_nop 0
	global_store_dwordx4 v[240:241], v[58:61], off
	v_add_u32_e32 v242, 0x63000, v32
	v_mov_b32_e32 v243, v33
	v_lshl_add_u64 v[242:243], v[242:243], 1, s[86:87]
	v_lshl_add_u64 v[242:243], v[242:243], 0, v[232:233]
	v_pk_mul_f32 v[158:159], v[46:47], s[18:19]
	v_pk_mul_f32 v[160:161], v[48:49], s[18:19]
	v_pk_mul_f32 v[162:163], v[38:39], s[18:19]
	v_pk_mul_f32 v[164:165], v[40:41], s[18:19]
	v_exp_f32_e32 v158, v158
	v_exp_f32_e32 v160, v160
	v_exp_f32_e32 v162, v162
	v_exp_f32_e32 v164, v164
	v_exp_f32_e32 v159, v159
	v_exp_f32_e32 v161, v161
	v_exp_f32_e32 v163, v163
	v_exp_f32_e32 v165, v165
	v_pk_add_f32 v[158:159], v[158:159], 1.0 op_sel_hi:[1,0]
	v_pk_add_f32 v[160:161], v[160:161], 1.0 op_sel_hi:[1,0]
	v_pk_add_f32 v[162:163], v[162:163], 1.0 op_sel_hi:[1,0]
	v_pk_add_f32 v[164:165], v[164:165], 1.0 op_sel_hi:[1,0]
	v_rcp_f32_e32 v158, v158
	v_rcp_f32_e32 v160, v160
	v_rcp_f32_e32 v162, v162
	v_rcp_f32_e32 v164, v164
	v_rcp_f32_e32 v159, v159
	v_rcp_f32_e32 v161, v161
	v_rcp_f32_e32 v163, v163
	v_rcp_f32_e32 v165, v165
	v_pk_mul_f32 v[158:159], v[46:47], v[158:159]
	v_pk_mul_f32 v[160:161], v[48:49], v[160:161]
	v_pk_mul_f32 v[162:163], v[38:39], v[162:163]
; __device__ __forceinline__ float silu_f(float x) { return x * __builtin_amdgcn_rcpf(1.0f + fexp(-x)); }
;     __device__ __forceinline__ void operator()(const f32x4 (&acc)[2][2][4][2], const Unit& u, int wr, int wc, int fr, int fq) const {
;         const int row0 = u.pm * BM + wr * 64 + fr, col0 = u.pn * 128 + wc * 32 + 8 * fq;
; #pragma unroll
;         for (int ai = 0; ai < 2; ++ai)
; #pragma unroll
;             for (int m = 0; m < 4; ++m) {
;                 h16x8 o;
; #pragma unroll
;                 for (int n = 0; n < 2; ++n)
; #pragma unroll
;                     for (int j = 0; j < 4; ++j) o[4 * n + j] = (h16)(silu_f(acc[ai][0][m][n][j]) * acc[ai][1][m][n][j]);
;                 *(h16x8*)(O + (unsigned)(row0 + ai * HALF + m * 16) * FF + col0) = o;
;             }
;     }
	v_pk_mul_f32 v[164:165], v[40:41], v[164:165]
	v_pk_mul_f32 v[158:159], v[158:159], v[42:43]
	v_pk_mul_f32 v[160:161], v[160:161], v[44:45]
	v_pk_mul_f32 v[162:163], v[162:163], v[34:35]
	v_pk_mul_f32 v[164:165], v[164:165], v[36:37]
	v_cvt_pk_f16_f32 v42, v158, v159
	v_cvt_pk_f16_f32 v43, v160, v161
	v_cvt_pk_f16_f32 v44, v162, v163
	v_cvt_pk_f16_f32 v45, v164, v165
	s_nop 0
	global_store_dwordx4 v[242:243], v[42:45], off
	v_add_u32_e32 v244, 0x6e000, v32
	v_mov_b32_e32 v245, v33
	v_lshl_add_u64 v[244:245], v[244:245], 1, s[86:87]
	v_lshl_add_u64 v[244:245], v[244:245], 0, v[232:233]
	v_pk_mul_f32 v[150:151], v[28:29], s[18:19]
	v_pk_mul_f32 v[152:153], v[30:31], s[18:19]
	v_pk_mul_f32 v[154:155], v[20:21], s[18:19]
	v_pk_mul_f32 v[156:157], v[22:23], s[18:19]
	v_exp_f32_e32 v150, v150
	v_exp_f32_e32 v152, v152
	v_exp_f32_e32 v154, v154
	v_exp_f32_e32 v156, v156
	v_exp_f32_e32 v151, v151
	v_exp_f32_e32 v153, v153
	v_exp_f32_e32 v155, v155
	v_exp_f32_e32 v157, v157
	v_pk_add_f32 v[150:151], v[150:151], 1.0 op_sel_hi:[1,0]
	v_pk_add_f32 v[152:153], v[152:153], 1.0 op_sel_hi:[1,0]
	v_pk_add_f32 v[154:155], v[154:155], 1.0 op_sel_hi:[1,0]
	v_pk_add_f32 v[156:157], v[156:157], 1.0 op_sel_hi:[1,0]
	v_rcp_f32_e32 v150, v150
	v_rcp_f32_e32 v152, v152
	v_rcp_f32_e32 v154, v154
	v_rcp_f32_e32 v156, v156
	v_rcp_f32_e32 v151, v151
	v_rcp_f32_e32 v153, v153
	v_rcp_f32_e32 v155, v155
	v_rcp_f32_e32 v157, v157
	v_pk_mul_f32 v[150:151], v[28:29], v[150:151]
	v_pk_mul_f32 v[152:153], v[30:31], v[152:153]
	v_pk_mul_f32 v[154:155], v[20:21], v[154:155]
	v_pk_mul_f32 v[156:157], v[22:23], v[156:157]
	v_pk_mul_f32 v[150:151], v[150:151], v[24:25]
	v_pk_mul_f32 v[152:153], v[152:153], v[26:27]
	v_pk_mul_f32 v[154:155], v[154:155], v[16:17]
	v_pk_mul_f32 v[156:157], v[156:157], v[18:19]
	v_cvt_pk_f16_f32 v24, v150, v151
	v_cvt_pk_f16_f32 v25, v152, v153
	v_cvt_pk_f16_f32 v26, v154, v155
	v_cvt_pk_f16_f32 v27, v156, v157
	s_nop 0
	global_store_dwordx4 v[244:245], v[24:27], off
	v_add_u32_e32 v32, 0x79000, v32
	v_lshl_add_u64 v[246:247], v[32:33], 1, s[86:87]
	v_lshl_add_u64 v[246:247], v[246:247], 0, v[232:233]
	v_pk_mul_f32 v[158:159], v[12:13], s[18:19]
	v_pk_mul_f32 v[160:161], v[14:15], s[18:19]
	v_pk_mul_f32 v[162:163], v[4:5], s[18:19]
	v_pk_mul_f32 v[164:165], v[6:7], s[18:19]
	v_exp_f32_e32 v158, v158
	v_exp_f32_e32 v160, v160
	v_exp_f32_e32 v162, v162
	v_exp_f32_e32 v164, v164
	v_exp_f32_e32 v159, v159
	v_exp_f32_e32 v161, v161
	v_exp_f32_e32 v163, v163
	v_exp_f32_e32 v165, v165
	v_pk_add_f32 v[158:159], v[158:159], 1.0 op_sel_hi:[1,0]
	v_pk_add_f32 v[160:161], v[160:161], 1.0 op_sel_hi:[1,0]
	v_pk_add_f32 v[162:163], v[162:163], 1.0 op_sel_hi:[1,0]
	v_pk_add_f32 v[164:165], v[164:165], 1.0 op_sel_hi:[1,0]
	v_rcp_f32_e32 v158, v158
	v_rcp_f32_e32 v160, v160
	v_rcp_f32_e32 v162, v162
	v_rcp_f32_e32 v164, v164
	v_rcp_f32_e32 v159, v159
	v_rcp_f32_e32 v161, v161
	v_rcp_f32_e32 v163, v163
	v_rcp_f32_e32 v165, v165
	v_pk_mul_f32 v[158:159], v[12:13], v[158:159]
	v_pk_mul_f32 v[160:161], v[14:15], v[160:161]
	v_pk_mul_f32 v[162:163], v[4:5], v[162:163]
	v_pk_mul_f32 v[164:165], v[6:7], v[164:165]
	v_pk_mul_f32 v[158:159], v[158:159], v[8:9]
	v_pk_mul_f32 v[160:161], v[160:161], v[10:11]
	v_pk_mul_f32 v[162:163], v[162:163], v[0:1]
	v_pk_mul_f32 v[164:165], v[164:165], v[2:3]
	v_cvt_pk_f16_f32 v8, v158, v159
	v_cvt_pk_f16_f32 v9, v160, v161
	v_cvt_pk_f16_f32 v10, v162, v163
	v_cvt_pk_f16_f32 v11, v164, v165
	s_nop 0
	global_store_dwordx4 v[246:247], v[8:11], off
	s_cbranch_vccnz .LBB0_749
	s_andn2_b64 vcc, exec, s[0:1]
	s_cbranch_vccnz .LBB0_748
	s_barrier
	s_branch .LBB0_748
